# speedup vs baseline: 1.0048x; 1.0023x over previous
; #define LDA(dst, b, h) for (int m = 0; m < 4; ++m) for (int k = 0; k < 2; ++k) \
;     dst[m][k] = *reinterpret_cast<const bf16x8*>((char*)SA(b, h) + lds_byte(wr * 64 + m * 16 + fr, k * 32 + fq * 8))
; #define LDB(dst, b, h) for (int n = 0; n < 2; ++n) for (int k = 0; k < 2; ++k) \
;     dst[n][k] = *reinterpret_cast<const bf16x8*>((char*)SB(b, h) + lds_byte(wc * 32 + n * 16 + fr, k * 32 + fq * 8))
; #define MMA(ai, bj, At, Bt_) do { __builtin_amdgcn_s_setprio(1); \
;     for (int m = 0; m < 4; ++m) for (int n = 0; n < 2; ++n) for (int k = 0; k < 2; ++k) \
;       acc[ai][bj][m][n] = __builtin_amdgcn_mfma_f32_16x16x32_bf16(At[m][k], Bt_[n][k], acc[ai][bj][m][n], 0, 0, 0); \
;     __builtin_amdgcn_s_setprio(0); } while (0)
; #define WAIT_V(n) asm volatile("s_waitcnt vmcnt(" #n ")" ::: "memory")
; #define WAIT_L(n) asm volatile("s_waitcnt lgkmcnt(" #n ")" ::: "memory")
; #define BAR __builtin_amdgcn_s_barrier()
; #define SCHED __builtin_amdgcn_sched_barrier(0)
; #define LDA(dst, b, h) for (int m = 0; m < 4; ++m) for (int k = 0; k < 2; ++k) \
;     dst[m][k] = *reinterpret_cast<const bf16x8*>((char*)SA(b, h) + lds_byte(wr * 64 + m * 16 + fr, k * 32 + fq * 8))
; #define LDB(dst, b, h) for (int n = 0; n < 2; ++n) for (int k = 0; k < 2; ++k) \
;     dst[n][k] = *reinterpret_cast<const bf16x8*>((char*)SB(b, h) + lds_byte(wc * 32 + n * 16 + fr, k * 32 + fq * 8))
; #define WAIT_V(n) asm volatile("s_waitcnt vmcnt(" #n ")" ::: "memory")
; #define WAIT_L(n) asm volatile("s_waitcnt lgkmcnt(" #n ")" ::: "memory")
; #define BAR __builtin_amdgcn_s_barrier()
; __device__ __forceinline__ void gemm8_rt(const PRef& p, const bf16* __restrict__ A, const bf16* __restrict__ Bt, const int K, const int N, const int epi, const int splitS, float* __restrict__ outp, bf16* shm) {
;     ...
;     for (int t = 0; t < nt - 2; t += 2) {
;       LDB(B0, 0, 0); SCHED; LDA(At, 0, 0); STAGE(SA(1, 1), A, brow + HALF, t + 1);
;       WAIT_L(8); BAR; WAIT_L(0); MMA(0, 0, At, B0); BAR; SCHED;
;       LDB(B1, 0, 1); STAGE(SB(0, 0), Bt, bcol, t + 2);
;       BAR; WAIT_L(0); MMA(0, 1, At, B1); BAR;
;       LDA(At, 0, 1); STAGE(SA(0, 0), A, brow, t + 2);
;       BAR; WAIT_L(0); MMA(1, 0, At, B0); BAR; SCHED;
;       STAGE(SB(0, 1), Bt, bcol + HALF, t + 2);
;       WAIT_V(6); BAR; MMA(1, 1, At, B1); BAR;
;       LDB(B0, 1, 0); SCHED; LDA(At, 1, 0); STAGE(SA(0, 1), A, brow + HALF, t + 2);
.LBB0_348:
	v_add_u32_e32 v0, v175, v174
	ds_read_b128 v[130:133], v0
	ds_read_b128 v[134:137], v0 offset:1024
	ds_read_b128 v[138:141], v0 offset:2048
	ds_read_b128 v[146:149], v0 offset:3072
	s_add_i32 s22, s4, s5
	v_add_u32_e32 v0, v183, v179
	v_add_u32_e32 v142, v184, v180
	v_add_u32_e32 v143, v184, v181
	v_add_u32_e32 v144, v184, v182
	s_add_i32 s18, s22, 0xffffff80
	s_mov_b32 m0, s55
	ds_read_b128 v[150:153], v0
	ds_read_b128 v[154:157], v0 offset:1024
	ds_read_b128 v[158:161], v142
	ds_read_b128 v[162:165], v142 offset:1024
	ds_read_b128 v[166:169], v143
	ds_read_b128 v[186:189], v143 offset:1024
	ds_read_b128 v[196:199], v144
	ds_read_b128 v[200:203], v144 offset:1024
	buffer_load_dwordx4 v172, s[76:79], s18 offen lds
	s_mov_b32 m0, s56
	s_nop 0
	buffer_load_dwordx4 v173, s[76:79], s18 offen lds
	s_waitcnt lgkmcnt(8)
	s_barrier
	s_waitcnt lgkmcnt(0)
	s_waitcnt lgkmcnt(7)
	v_mfma_f32_16x16x32_bf16 v[126:129], v[150:153], v[130:133], v[126:129]
	v_mfma_f32_16x16x32_bf16 v[122:125], v[150:153], v[138:141], v[122:125]
	s_waitcnt lgkmcnt(5)
	v_mfma_f32_16x16x32_bf16 v[118:121], v[158:161], v[130:133], v[118:121]
	v_mfma_f32_16x16x32_bf16 v[114:117], v[158:161], v[138:141], v[114:117]
	s_waitcnt lgkmcnt(3)
	v_mfma_f32_16x16x32_bf16 v[110:113], v[166:169], v[130:133], v[110:113]
	v_mfma_f32_16x16x32_bf16 v[106:109], v[166:169], v[138:141], v[106:109]
	s_waitcnt lgkmcnt(1)
	v_mfma_f32_16x16x32_bf16 v[102:105], v[196:199], v[130:133], v[102:105]
	v_mfma_f32_16x16x32_bf16 v[98:101], v[196:199], v[138:141], v[98:101]
	v_mfma_f32_16x16x32_bf16 v[126:129], v[154:157], v[134:137], v[126:129]
	v_mfma_f32_16x16x32_bf16 v[122:125], v[154:157], v[146:149], v[122:125]
	v_mfma_f32_16x16x32_bf16 v[118:121], v[162:165], v[134:137], v[118:121]
	v_mfma_f32_16x16x32_bf16 v[114:117], v[162:165], v[146:149], v[114:117]
	v_mfma_f32_16x16x32_bf16 v[110:113], v[186:189], v[134:137], v[110:113]
	v_mfma_f32_16x16x32_bf16 v[106:109], v[186:189], v[146:149], v[106:109]
	s_waitcnt lgkmcnt(0)
	v_mfma_f32_16x16x32_bf16 v[102:105], v[200:203], v[134:137], v[102:105]
	v_mfma_f32_16x16x32_bf16 v[98:101], v[200:203], v[146:149], v[98:101]
	s_barrier
	s_add_i32 s23, s4, s12
	s_mov_b32 m0, s57
	v_add_u32_e32 v185, v176, v174
	s_add_i32 s27, s23, 0x100
	s_mov_b32 s18, s78
	s_mov_b32 s19, s79
	ds_read_b128 v[204:207], v185
	ds_read_b128 v[212:215], v185 offset:1024
	ds_read_b128 v[216:219], v185 offset:2048
	ds_read_b128 v[220:223], v185 offset:3072
	buffer_load_dwordx4 v172, s[16:19], s27 offen lds
	s_mov_b32 m0, s58
	s_add_i32 s13, s13, 2
	buffer_load_dwordx4 v173, s[16:19], s27 offen lds
	s_barrier
	s_waitcnt lgkmcnt(0)
	s_waitcnt lgkmcnt(3)
	v_mfma_f32_16x16x32_bf16 v[94:97], v[150:153], v[204:207], v[94:97]
	s_waitcnt lgkmcnt(1)
	v_mfma_f32_16x16x32_bf16 v[90:93], v[150:153], v[216:219], v[90:93]
	v_mfma_f32_16x16x32_bf16 v[86:89], v[158:161], v[204:207], v[86:89]
	v_mfma_f32_16x16x32_bf16 v[82:85], v[158:161], v[216:219], v[82:85]
	v_mfma_f32_16x16x32_bf16 v[78:81], v[166:169], v[204:207], v[78:81]
	v_mfma_f32_16x16x32_bf16 v[74:77], v[166:169], v[216:219], v[74:77]
	v_mfma_f32_16x16x32_bf16 v[70:73], v[196:199], v[204:207], v[70:73]
	v_mfma_f32_16x16x32_bf16 v[66:69], v[196:199], v[216:219], v[66:69]
	v_mfma_f32_16x16x32_bf16 v[94:97], v[154:157], v[212:215], v[94:97]
	s_waitcnt lgkmcnt(0)
	v_mfma_f32_16x16x32_bf16 v[90:93], v[154:157], v[220:223], v[90:93]
	v_mfma_f32_16x16x32_bf16 v[86:89], v[162:165], v[212:215], v[86:89]
	v_mfma_f32_16x16x32_bf16 v[82:85], v[162:165], v[220:223], v[82:85]
	v_mfma_f32_16x16x32_bf16 v[78:81], v[186:189], v[212:215], v[78:81]
	v_mfma_f32_16x16x32_bf16 v[74:77], v[186:189], v[220:223], v[74:77]
	v_mfma_f32_16x16x32_bf16 v[70:73], v[200:203], v[212:215], v[70:73]
	v_mfma_f32_16x16x32_bf16 v[66:69], v[200:203], v[220:223], v[66:69]
	s_add_i32 s27, s4, s11
	s_add_i32 s29, s27, 0x100
	s_mov_b32 m0, s50
	s_barrier
	ds_read_b128 v[150:153], v0 offset:16384
	ds_read_b128 v[154:157], v0 offset:17408
	ds_read_b128 v[158:161], v142 offset:16384
	ds_read_b128 v[162:165], v142 offset:17408
	ds_read_b128 v[166:169], v143 offset:16384
	ds_read_b128 v[186:189], v143 offset:17408
	ds_read_b128 v[196:199], v144 offset:16384
	ds_read_b128 v[200:203], v144 offset:17408
	buffer_load_dwordx4 v172, s[76:79], s29 offen lds
	s_mov_b32 m0, s59
	s_nop 0
	buffer_load_dwordx4 v173, s[76:79], s29 offen lds
	s_barrier
	s_waitcnt lgkmcnt(0)
	s_waitcnt lgkmcnt(7)
	v_mfma_f32_16x16x32_bf16 v[62:65], v[150:153], v[130:133], v[62:65]
	v_mfma_f32_16x16x32_bf16 v[58:61], v[150:153], v[138:141], v[58:61]
	s_waitcnt lgkmcnt(5)
	v_mfma_f32_16x16x32_bf16 v[54:57], v[158:161], v[130:133], v[54:57]
	v_mfma_f32_16x16x32_bf16 v[50:53], v[158:161], v[138:141], v[50:53]
	s_waitcnt lgkmcnt(3)
	v_mfma_f32_16x16x32_bf16 v[46:49], v[166:169], v[130:133], v[46:49]
	v_mfma_f32_16x16x32_bf16 v[42:45], v[166:169], v[138:141], v[42:45]
	s_waitcnt lgkmcnt(1)
	v_mfma_f32_16x16x32_bf16 v[38:41], v[196:199], v[130:133], v[38:41]
	v_mfma_f32_16x16x32_bf16 v[34:37], v[196:199], v[138:141], v[34:37]
	v_mfma_f32_16x16x32_bf16 v[62:65], v[154:157], v[134:137], v[62:65]
	v_mfma_f32_16x16x32_bf16 v[58:61], v[154:157], v[146:149], v[58:61]
	v_mfma_f32_16x16x32_bf16 v[54:57], v[162:165], v[134:137], v[54:57]
	v_mfma_f32_16x16x32_bf16 v[50:53], v[162:165], v[146:149], v[50:53]
	v_mfma_f32_16x16x32_bf16 v[46:49], v[186:189], v[134:137], v[46:49]
	v_mfma_f32_16x16x32_bf16 v[42:45], v[186:189], v[146:149], v[42:45]
	s_waitcnt lgkmcnt(0)
	v_mfma_f32_16x16x32_bf16 v[38:41], v[200:203], v[134:137], v[38:41]
	v_mfma_f32_16x16x32_bf16 v[34:37], v[200:203], v[146:149], v[34:37]
	s_barrier
; #define LDA(dst, b, h) for (int m = 0; m < 4; ++m) for (int k = 0; k < 2; ++k) \
;     dst[m][k] = *reinterpret_cast<const bf16x8*>((char*)SA(b, h) + lds_byte(wr * 64 + m * 16 + fr, k * 32 + fq * 8))
; #define LDB(dst, b, h) for (int n = 0; n < 2; ++n) for (int k = 0; k < 2; ++k) \
;     dst[n][k] = *reinterpret_cast<const bf16x8*>((char*)SB(b, h) + lds_byte(wc * 32 + n * 16 + fr, k * 32 + fq * 8))
; #define MMA(ai, bj, At, Bt_) do { __builtin_amdgcn_s_setprio(1); \
;     for (int m = 0; m < 4; ++m) for (int n = 0; n < 2; ++n) for (int k = 0; k < 2; ++k) \
;       acc[ai][bj][m][n] = __builtin_amdgcn_mfma_f32_16x16x32_bf16(At[m][k], Bt_[n][k], acc[ai][bj][m][n], 0, 0, 0); \
;     __builtin_amdgcn_s_setprio(0); } while (0)
; #define WAIT_V(n) asm volatile("s_waitcnt vmcnt(" #n ")" ::: "memory")
; #define WAIT_L(n) asm volatile("s_waitcnt lgkmcnt(" #n ")" ::: "memory")
; #define BAR __builtin_amdgcn_s_barrier()
; #define SCHED __builtin_amdgcn_sched_barrier(0)
; #define LDA(dst, b, h) for (int m = 0; m < 4; ++m) for (int k = 0; k < 2; ++k) \
;     dst[m][k] = *reinterpret_cast<const bf16x8*>((char*)SA(b, h) + lds_byte(wr * 64 + m * 16 + fr, k * 32 + fq * 8))
; #define LDB(dst, b, h) for (int n = 0; n < 2; ++n) for (int k = 0; k < 2; ++k) \
;     dst[n][k] = *reinterpret_cast<const bf16x8*>((char*)SB(b, h) + lds_byte(wc * 32 + n * 16 + fr, k * 32 + fq * 8))
; #define MMA(ai, bj, At, Bt_) do { __builtin_amdgcn_s_setprio(1); \
;     for (int m = 0; m < 4; ++m) for (int n = 0; n < 2; ++n) for (int k = 0; k < 2; ++k) \
;       acc[ai][bj][m][n] = __builtin_amdgcn_mfma_f32_16x16x32_bf16(At[m][k], Bt_[n][k], acc[ai][bj][m][n], 0, 0, 0); \
;     __builtin_amdgcn_s_setprio(0); } while (0)
; __device__ __forceinline__ void gemm8_rt(const PRef& p, const bf16* __restrict__ A, const bf16* __restrict__ Bt, const int K, const int N, const int epi, const int splitS, float* __restrict__ outp, bf16* shm) {
;     ...
;       STAGE(SB(0, 1), Bt, bcol + HALF, t + 2);
;       WAIT_V(6); BAR; MMA(1, 1, At, B1); BAR;
;       LDB(B0, 1, 0); SCHED; LDA(At, 1, 0); STAGE(SA(0, 1), A, brow + HALF, t + 2);
;       WAIT_L(8); BAR; WAIT_L(0); MMA(0, 0, At, B0); BAR; SCHED;
;       LDB(B1, 1, 1); STAGE(SB(1, 0), Bt, bcol, t + 3);
;       BAR; WAIT_L(0); MMA(0, 1, At, B1); BAR;
;       LDA(At, 1, 1); STAGE(SA(1, 0), A, brow, t + 3);
;       BAR; WAIT_L(0); MMA(1, 0, At, B0); BAR; SCHED;
	s_add_i32 s29, s4, s10
	s_add_i32 s30, s29, 0x100
	s_mov_b32 m0, s60
	s_nop 0
	buffer_load_dwordx4 v172, s[16:19], s30 offen lds
	s_mov_b32 m0, s61
	s_nop 0
	buffer_load_dwordx4 v173, s[16:19], s30 offen lds
	s_waitcnt vmcnt(6)
	s_barrier
	v_mfma_f32_16x16x32_bf16 v[30:33], v[150:153], v[204:207], v[30:33]
	v_mfma_f32_16x16x32_bf16 v[26:29], v[150:153], v[216:219], v[26:29]
	v_mfma_f32_16x16x32_bf16 v[22:25], v[158:161], v[204:207], v[22:25]
	v_mfma_f32_16x16x32_bf16 v[18:21], v[158:161], v[216:219], v[18:21]
	v_mfma_f32_16x16x32_bf16 v[14:17], v[166:169], v[204:207], v[14:17]
	v_mfma_f32_16x16x32_bf16 v[10:13], v[166:169], v[216:219], v[10:13]
	v_mfma_f32_16x16x32_bf16 v[6:9], v[196:199], v[204:207], v[6:9]
	v_mfma_f32_16x16x32_bf16 v[2:5], v[196:199], v[216:219], v[2:5]
	v_mfma_f32_16x16x32_bf16 v[30:33], v[154:157], v[212:215], v[30:33]
	v_mfma_f32_16x16x32_bf16 v[26:29], v[154:157], v[220:223], v[26:29]
	v_mfma_f32_16x16x32_bf16 v[22:25], v[162:165], v[212:215], v[22:25]
	v_mfma_f32_16x16x32_bf16 v[18:21], v[162:165], v[220:223], v[18:21]
	v_mfma_f32_16x16x32_bf16 v[14:17], v[186:189], v[212:215], v[14:17]
	v_mfma_f32_16x16x32_bf16 v[10:13], v[186:189], v[220:223], v[10:13]
	v_mfma_f32_16x16x32_bf16 v[6:9], v[200:203], v[212:215], v[6:9]
	v_mfma_f32_16x16x32_bf16 v[2:5], v[200:203], v[220:223], v[2:5]
	v_add_u32_e32 v146, v177, v174
	s_barrier
	ds_read_b128 v[130:133], v146
	ds_read_b128 v[134:137], v146 offset:1024
	ds_read_b128 v[138:141], v146 offset:2048
	ds_read_b128 v[146:149], v146 offset:3072
	s_mov_b32 m0, s62
	ds_read_b128 v[150:153], v0 offset:32768
	ds_read_b128 v[154:157], v0 offset:33792
	ds_read_b128 v[158:161], v142 offset:32768
	ds_read_b128 v[162:165], v142 offset:33792
	ds_read_b128 v[166:169], v143 offset:32768
	ds_read_b128 v[186:189], v143 offset:33792
	ds_read_b128 v[196:199], v144 offset:32768
	ds_read_b128 v[200:203], v144 offset:33792
	buffer_load_dwordx4 v172, s[76:79], s22 offen lds
	s_mov_b32 m0, s63
	s_nop 0
	buffer_load_dwordx4 v173, s[76:79], s22 offen lds
	s_waitcnt lgkmcnt(8)
	s_barrier
	s_waitcnt lgkmcnt(0)
	s_waitcnt lgkmcnt(7)
	v_mfma_f32_16x16x32_bf16 v[126:129], v[150:153], v[130:133], v[126:129]
	v_mfma_f32_16x16x32_bf16 v[122:125], v[150:153], v[138:141], v[122:125]
	s_waitcnt lgkmcnt(5)
	v_mfma_f32_16x16x32_bf16 v[118:121], v[158:161], v[130:133], v[118:121]
	v_mfma_f32_16x16x32_bf16 v[114:117], v[158:161], v[138:141], v[114:117]
	s_waitcnt lgkmcnt(3)
	v_mfma_f32_16x16x32_bf16 v[110:113], v[166:169], v[130:133], v[110:113]
	v_mfma_f32_16x16x32_bf16 v[106:109], v[166:169], v[138:141], v[106:109]
	s_waitcnt lgkmcnt(1)
	v_mfma_f32_16x16x32_bf16 v[102:105], v[196:199], v[130:133], v[102:105]
	v_mfma_f32_16x16x32_bf16 v[98:101], v[196:199], v[138:141], v[98:101]
	v_mfma_f32_16x16x32_bf16 v[126:129], v[154:157], v[134:137], v[126:129]
	v_mfma_f32_16x16x32_bf16 v[122:125], v[154:157], v[146:149], v[122:125]
	v_mfma_f32_16x16x32_bf16 v[118:121], v[162:165], v[134:137], v[118:121]
	v_mfma_f32_16x16x32_bf16 v[114:117], v[162:165], v[146:149], v[114:117]
	v_mfma_f32_16x16x32_bf16 v[110:113], v[186:189], v[134:137], v[110:113]
	v_mfma_f32_16x16x32_bf16 v[106:109], v[186:189], v[146:149], v[106:109]
	s_waitcnt lgkmcnt(0)
	v_mfma_f32_16x16x32_bf16 v[102:105], v[200:203], v[134:137], v[102:105]
	v_mfma_f32_16x16x32_bf16 v[98:101], v[200:203], v[146:149], v[98:101]
	s_barrier
	v_add_u32_e32 v185, v178, v174
	s_addk_i32 s23, 0x180
	s_mov_b32 m0, s48
	ds_read_b128 v[204:207], v185
	ds_read_b128 v[212:215], v185 offset:1024
	ds_read_b128 v[216:219], v185 offset:2048
	ds_read_b128 v[220:223], v185 offset:3072
	buffer_load_dwordx4 v172, s[16:19], s23 offen lds
	s_mov_b32 m0, s49
	s_nop 0
	buffer_load_dwordx4 v173, s[16:19], s23 offen lds
	s_barrier
	s_waitcnt lgkmcnt(0)
	s_waitcnt lgkmcnt(3)
	v_mfma_f32_16x16x32_bf16 v[94:97], v[150:153], v[204:207], v[94:97]
	s_waitcnt lgkmcnt(1)
	v_mfma_f32_16x16x32_bf16 v[90:93], v[150:153], v[216:219], v[90:93]
	v_mfma_f32_16x16x32_bf16 v[86:89], v[158:161], v[204:207], v[86:89]
	v_mfma_f32_16x16x32_bf16 v[82:85], v[158:161], v[216:219], v[82:85]
	v_mfma_f32_16x16x32_bf16 v[78:81], v[166:169], v[204:207], v[78:81]
	v_mfma_f32_16x16x32_bf16 v[74:77], v[166:169], v[216:219], v[74:77]
	v_mfma_f32_16x16x32_bf16 v[70:73], v[196:199], v[204:207], v[70:73]
	v_mfma_f32_16x16x32_bf16 v[66:69], v[196:199], v[216:219], v[66:69]
	v_mfma_f32_16x16x32_bf16 v[94:97], v[154:157], v[212:215], v[94:97]
	s_waitcnt lgkmcnt(0)
	v_mfma_f32_16x16x32_bf16 v[90:93], v[154:157], v[220:223], v[90:93]
	v_mfma_f32_16x16x32_bf16 v[86:89], v[162:165], v[212:215], v[86:89]
	v_mfma_f32_16x16x32_bf16 v[82:85], v[162:165], v[220:223], v[82:85]
	v_mfma_f32_16x16x32_bf16 v[78:81], v[186:189], v[212:215], v[78:81]
	v_mfma_f32_16x16x32_bf16 v[74:77], v[186:189], v[220:223], v[74:77]
	v_mfma_f32_16x16x32_bf16 v[70:73], v[200:203], v[212:215], v[70:73]
	v_mfma_f32_16x16x32_bf16 v[66:69], v[200:203], v[220:223], v[66:69]
	s_addk_i32 s27, 0x180
	s_mov_b32 m0, s51
	s_barrier
	ds_read_b128 v[150:153], v0 offset:49152
	ds_read_b128 v[154:157], v0 offset:50176
	ds_read_b128 v[158:161], v142 offset:49152
	ds_read_b128 v[162:165], v142 offset:50176
	ds_read_b128 v[166:169], v143 offset:49152
	ds_read_b128 v[186:189], v143 offset:50176
	ds_read_b128 v[196:199], v144 offset:49152
	ds_read_b128 v[200:203], v144 offset:50176
	buffer_load_dwordx4 v172, s[76:79], s27 offen lds
	s_mov_b32 m0, s52
	s_nop 0
	buffer_load_dwordx4 v173, s[76:79], s27 offen lds
	s_barrier
; #define LDA(dst, b, h) for (int m = 0; m < 4; ++m) for (int k = 0; k < 2; ++k) \
;     dst[m][k] = *reinterpret_cast<const bf16x8*>((char*)SA(b, h) + lds_byte(wr * 64 + m * 16 + fr, k * 32 + fq * 8))
; #define LDB(dst, b, h) for (int n = 0; n < 2; ++n) for (int k = 0; k < 2; ++k) \
;     dst[n][k] = *reinterpret_cast<const bf16x8*>((char*)SB(b, h) + lds_byte(wc * 32 + n * 16 + fr, k * 32 + fq * 8))
; #define MMA(ai, bj, At, Bt_) do { __builtin_amdgcn_s_setprio(1); \
;     for (int m = 0; m < 4; ++m) for (int n = 0; n < 2; ++n) for (int k = 0; k < 2; ++k) \
;       acc[ai][bj][m][n] = __builtin_amdgcn_mfma_f32_16x16x32_bf16(At[m][k], Bt_[n][k], acc[ai][bj][m][n], 0, 0, 0); \
;     __builtin_amdgcn_s_setprio(0); } while (0)
; #define WAIT_V(n) asm volatile("s_waitcnt vmcnt(" #n ")" ::: "memory")
; #define WAIT_L(n) asm volatile("s_waitcnt lgkmcnt(" #n ")" ::: "memory")
; #define BAR __builtin_amdgcn_s_barrier()
; #define SCHED __builtin_amdgcn_sched_barrier(0)
; #define LDA(dst, b, h) for (int m = 0; m < 4; ++m) for (int k = 0; k < 2; ++k) \
;     dst[m][k] = *reinterpret_cast<const bf16x8*>((char*)SA(b, h) + lds_byte(wr * 64 + m * 16 + fr, k * 32 + fq * 8))
; #define LDB(dst, b, h) for (int n = 0; n < 2; ++n) for (int k = 0; k < 2; ++k) \
;     dst[n][k] = *reinterpret_cast<const bf16x8*>((char*)SB(b, h) + lds_byte(wc * 32 + n * 16 + fr, k * 32 + fq * 8))
; #define MMA(ai, bj, At, Bt_) do { __builtin_amdgcn_s_setprio(1); \
;     for (int m = 0; m < 4; ++m) for (int n = 0; n < 2; ++n) for (int k = 0; k < 2; ++k) \
;       acc[ai][bj][m][n] = __builtin_amdgcn_mfma_f32_16x16x32_bf16(At[m][k], Bt_[n][k], acc[ai][bj][m][n], 0, 0, 0); \
;     __builtin_amdgcn_s_setprio(0); } while (0)
; __device__ __forceinline__ void gemm8_rt(const PRef& p, const bf16* __restrict__ A, const bf16* __restrict__ Bt, const int K, const int N, const int epi, const int splitS, float* __restrict__ outp, bf16* shm) {
;     ...
;       BAR; WAIT_L(0); MMA(1, 0, At, B0); BAR; SCHED;
;       STAGE(SB(1, 1), Bt, bcol + HALF, t + 3);
;       WAIT_V(6); BAR; MMA(1, 1, At, B1); BAR;
;     }
;     { LDB(B0, 0, 0); LDA(At, 0, 0); STAGE(SA(1, 1), A, brow + HALF, nt - 1);
;       BAR; WAIT_L(0); MMA(0, 0, At, B0); BAR;
;       LDB(B1, 0, 1); BAR; WAIT_L(0); MMA(0, 1, At, B1); BAR;
;       LDA(At, 0, 1); WAIT_V(4); BAR; WAIT_L(0); MMA(1, 0, At, B0); MMA(1, 1, At, B1); BAR; }
	s_waitcnt lgkmcnt(0)
	s_waitcnt lgkmcnt(7)
	v_mfma_f32_16x16x32_bf16 v[62:65], v[150:153], v[130:133], v[62:65]
	v_mfma_f32_16x16x32_bf16 v[58:61], v[150:153], v[138:141], v[58:61]
	s_waitcnt lgkmcnt(5)
	v_mfma_f32_16x16x32_bf16 v[54:57], v[158:161], v[130:133], v[54:57]
	v_mfma_f32_16x16x32_bf16 v[50:53], v[158:161], v[138:141], v[50:53]
	s_waitcnt lgkmcnt(3)
	v_mfma_f32_16x16x32_bf16 v[46:49], v[166:169], v[130:133], v[46:49]
	v_mfma_f32_16x16x32_bf16 v[42:45], v[166:169], v[138:141], v[42:45]
	s_waitcnt lgkmcnt(1)
	v_mfma_f32_16x16x32_bf16 v[38:41], v[196:199], v[130:133], v[38:41]
	v_mfma_f32_16x16x32_bf16 v[34:37], v[196:199], v[138:141], v[34:37]
	v_mfma_f32_16x16x32_bf16 v[62:65], v[154:157], v[134:137], v[62:65]
	v_mfma_f32_16x16x32_bf16 v[58:61], v[154:157], v[146:149], v[58:61]
	v_mfma_f32_16x16x32_bf16 v[54:57], v[162:165], v[134:137], v[54:57]
	v_mfma_f32_16x16x32_bf16 v[50:53], v[162:165], v[146:149], v[50:53]
	v_mfma_f32_16x16x32_bf16 v[46:49], v[186:189], v[134:137], v[46:49]
	v_mfma_f32_16x16x32_bf16 v[42:45], v[186:189], v[146:149], v[42:45]
	s_waitcnt lgkmcnt(0)
	v_mfma_f32_16x16x32_bf16 v[38:41], v[200:203], v[134:137], v[38:41]
	v_mfma_f32_16x16x32_bf16 v[34:37], v[200:203], v[146:149], v[34:37]
	s_barrier
	s_addk_i32 s29, 0x180
	s_mov_b32 m0, s53
	s_nop 0
	buffer_load_dwordx4 v172, s[16:19], s29 offen lds
	s_mov_b32 m0, s54
	s_nop 0
	buffer_load_dwordx4 v173, s[16:19], s29 offen lds
	s_waitcnt vmcnt(6)
	s_barrier
	v_mfma_f32_16x16x32_bf16 v[30:33], v[150:153], v[204:207], v[30:33]
	v_mfma_f32_16x16x32_bf16 v[26:29], v[150:153], v[216:219], v[26:29]
	v_mfma_f32_16x16x32_bf16 v[22:25], v[158:161], v[204:207], v[22:25]
	v_mfma_f32_16x16x32_bf16 v[18:21], v[158:161], v[216:219], v[18:21]
	v_mfma_f32_16x16x32_bf16 v[14:17], v[166:169], v[204:207], v[14:17]
	v_mfma_f32_16x16x32_bf16 v[10:13], v[166:169], v[216:219], v[10:13]
	v_mfma_f32_16x16x32_bf16 v[6:9], v[196:199], v[204:207], v[6:9]
	v_mfma_f32_16x16x32_bf16 v[2:5], v[196:199], v[216:219], v[2:5]
	v_mfma_f32_16x16x32_bf16 v[30:33], v[154:157], v[212:215], v[30:33]
	v_mfma_f32_16x16x32_bf16 v[26:29], v[154:157], v[220:223], v[26:29]
	v_mfma_f32_16x16x32_bf16 v[22:25], v[162:165], v[212:215], v[22:25]
	v_mfma_f32_16x16x32_bf16 v[18:21], v[162:165], v[220:223], v[18:21]
	v_mfma_f32_16x16x32_bf16 v[14:17], v[186:189], v[212:215], v[14:17]
	v_mfma_f32_16x16x32_bf16 v[10:13], v[186:189], v[220:223], v[10:13]
	v_mfma_f32_16x16x32_bf16 v[6:9], v[200:203], v[212:215], v[6:9]
	v_mfma_f32_16x16x32_bf16 v[2:5], v[200:203], v[220:223], v[2:5]
	s_addk_i32 s5, 0x100
	s_addk_i32 s10, 0x100
	s_addk_i32 s11, 0x100
	s_addk_i32 s12, 0x100
	s_cmp_ge_i32 s13, s1
	s_barrier
	s_cbranch_scc0 .LBB0_348
.LBB0_349:
	s_add_i32 s0, s0, s66
	s_add_i32 s0, s46, s0
	s_lshl_b32 s0, s0, 1
	s_lshl_b32 s1, s47, 7
	v_add_u32_e32 v0, v175, v174
	s_add_i32 s0, s0, s1
	ds_read_b128 v[130:133], v0
	ds_read_b128 v[134:137], v0 offset:1024
	ds_read_b128 v[138:141], v0 offset:2048
	ds_read_b128 v[146:149], v0 offset:3072
	v_add_u32_e32 v0, v183, v179
	v_add_u32_e32 v142, v184, v180
	v_add_u32_e32 v143, v184, v181
	v_add_u32_e32 v144, v184, v182
	s_addk_i32 s0, 0xff80
	s_mov_b32 m0, s55
	ds_read_b128 v[150:153], v0
	ds_read_b128 v[154:157], v0 offset:1024
	ds_read_b128 v[158:161], v142
	ds_read_b128 v[162:165], v142 offset:1024
	ds_read_b128 v[166:169], v143
	ds_read_b128 v[186:189], v143 offset:1024
	ds_read_b128 v[212:215], v144
	ds_read_b128 v[216:219], v144 offset:1024
	buffer_load_dwordx4 v172, s[76:79], s0 offen lds
	s_mov_b32 m0, s56
	s_nop 0
	buffer_load_dwordx4 v173, s[76:79], s0 offen lds
	s_barrier
	s_waitcnt lgkmcnt(0)
	s_waitcnt lgkmcnt(7)
	v_mfma_f32_16x16x32_bf16 v[126:129], v[150:153], v[130:133], v[126:129]
	v_mfma_f32_16x16x32_bf16 v[122:125], v[150:153], v[138:141], v[122:125]
	s_waitcnt lgkmcnt(3)
	v_mfma_f32_16x16x32_bf16 v[110:113], v[166:169], v[130:133], v[110:113]
	v_mfma_f32_16x16x32_bf16 v[106:109], v[166:169], v[138:141], v[106:109]
	v_mfma_f32_16x16x32_bf16 v[126:129], v[154:157], v[134:137], v[126:129]
	v_mfma_f32_16x16x32_bf16 v[122:125], v[154:157], v[146:149], v[122:125]
	v_mfma_f32_16x16x32_bf16 v[118:121], v[158:161], v[130:133], v[118:121]
	v_mfma_f32_16x16x32_bf16 v[114:117], v[158:161], v[138:141], v[114:117]
	s_waitcnt lgkmcnt(2)
	v_mfma_f32_16x16x32_bf16 v[110:113], v[186:189], v[134:137], v[110:113]
	v_mfma_f32_16x16x32_bf16 v[106:109], v[186:189], v[146:149], v[106:109]
	s_waitcnt lgkmcnt(1)
	v_mfma_f32_16x16x32_bf16 v[102:105], v[212:215], v[130:133], v[102:105]
	v_mfma_f32_16x16x32_bf16 v[98:101], v[212:215], v[138:141], v[98:101]
	v_mfma_f32_16x16x32_bf16 v[220:223], v[162:165], v[134:137], v[118:121]
	v_mfma_f32_16x16x32_bf16 v[224:227], v[162:165], v[146:149], v[114:117]
	s_waitcnt lgkmcnt(0)
	v_mfma_f32_16x16x32_bf16 v[228:231], v[216:219], v[134:137], v[102:105]
	v_mfma_f32_16x16x32_bf16 v[232:235], v[216:219], v[146:149], v[98:101]
	v_add_u32_e32 v118, v176, v174
	s_barrier
	ds_read_b128 v[98:101], v118
	ds_read_b128 v[102:105], v118 offset:1024
	ds_read_b128 v[114:117], v118 offset:2048
	ds_read_b128 v[118:121], v118 offset:3072
	s_barrier
; #define LDA(dst, b, h) for (int m = 0; m < 4; ++m) for (int k = 0; k < 2; ++k) \
;     dst[m][k] = *reinterpret_cast<const bf16x8*>((char*)SA(b, h) + lds_byte(wr * 64 + m * 16 + fr, k * 32 + fq * 8))
; #define LDB(dst, b, h) for (int n = 0; n < 2; ++n) for (int k = 0; k < 2; ++k) \
;     dst[n][k] = *reinterpret_cast<const bf16x8*>((char*)SB(b, h) + lds_byte(wc * 32 + n * 16 + fr, k * 32 + fq * 8))
; #define MMA(ai, bj, At, Bt_) do { __builtin_amdgcn_s_setprio(1); \
;     for (int m = 0; m < 4; ++m) for (int n = 0; n < 2; ++n) for (int k = 0; k < 2; ++k) \
;       acc[ai][bj][m][n] = __builtin_amdgcn_mfma_f32_16x16x32_bf16(At[m][k], Bt_[n][k], acc[ai][bj][m][n], 0, 0, 0); \
;     __builtin_amdgcn_s_setprio(0); } while (0)
; #define WAIT_V(n) asm volatile("s_waitcnt vmcnt(" #n ")" ::: "memory")
; #define WAIT_L(n) asm volatile("s_waitcnt lgkmcnt(" #n ")" ::: "memory")
; #define BAR __builtin_amdgcn_s_barrier()
; #define LDA(dst, b, h) for (int m = 0; m < 4; ++m) for (int k = 0; k < 2; ++k) \
;     dst[m][k] = *reinterpret_cast<const bf16x8*>((char*)SA(b, h) + lds_byte(wr * 64 + m * 16 + fr, k * 32 + fq * 8))
; #define LDB(dst, b, h) for (int n = 0; n < 2; ++n) for (int k = 0; k < 2; ++k) \
;     dst[n][k] = *reinterpret_cast<const bf16x8*>((char*)SB(b, h) + lds_byte(wc * 32 + n * 16 + fr, k * 32 + fq * 8))
; #define MMA(ai, bj, At, Bt_) do { __builtin_amdgcn_s_setprio(1); \
;     for (int m = 0; m < 4; ++m) for (int n = 0; n < 2; ++n) for (int k = 0; k < 2; ++k) \
;       acc[ai][bj][m][n] = __builtin_amdgcn_mfma_f32_16x16x32_bf16(At[m][k], Bt_[n][k], acc[ai][bj][m][n], 0, 0, 0); \
;     __builtin_amdgcn_s_setprio(0); } while (0)
; #define WAIT_V(n) asm volatile("s_waitcnt vmcnt(" #n ")" ::: "memory")
; #define WAIT_L(n) asm volatile("s_waitcnt lgkmcnt(" #n ")" ::: "memory")
; #define BAR __builtin_amdgcn_s_barrier()
; __device__ __forceinline__ void gemm8_rt(const PRef& p, const bf16* __restrict__ A, const bf16* __restrict__ Bt, const int K, const int N, const int epi, const int splitS, float* __restrict__ outp, bf16* shm) {
;     ...
;       LDB(B1, 0, 1); BAR; WAIT_L(0); MMA(0, 1, At, B1); BAR;
;       LDA(At, 0, 1); WAIT_V(4); BAR; WAIT_L(0); MMA(1, 0, At, B0); MMA(1, 1, At, B1); BAR; }
;     { LDB(B0, 1, 0); LDA(At, 1, 0); WAIT_V(2); BAR; WAIT_L(0); MMA(0, 0, At, B0); BAR;
;       LDB(B1, 1, 1); WAIT_V(0); BAR; WAIT_L(0); MMA(0, 1, At, B1); BAR;
	s_waitcnt lgkmcnt(0)
	s_waitcnt lgkmcnt(3)
	v_mfma_f32_16x16x32_bf16 v[94:97], v[150:153], v[98:101], v[94:97]
	s_waitcnt lgkmcnt(1)
	v_mfma_f32_16x16x32_bf16 v[90:93], v[150:153], v[114:117], v[90:93]
	v_mfma_f32_16x16x32_bf16 v[78:81], v[166:169], v[98:101], v[78:81]
	v_mfma_f32_16x16x32_bf16 v[74:77], v[166:169], v[114:117], v[74:77]
	v_mfma_f32_16x16x32_bf16 v[94:97], v[154:157], v[102:105], v[94:97]
	s_waitcnt lgkmcnt(0)
	v_mfma_f32_16x16x32_bf16 v[90:93], v[154:157], v[118:121], v[90:93]
	v_mfma_f32_16x16x32_bf16 v[86:89], v[158:161], v[98:101], v[86:89]
	v_mfma_f32_16x16x32_bf16 v[82:85], v[158:161], v[114:117], v[82:85]
	v_mfma_f32_16x16x32_bf16 v[78:81], v[186:189], v[102:105], v[78:81]
	v_mfma_f32_16x16x32_bf16 v[74:77], v[186:189], v[118:121], v[74:77]
	v_mfma_f32_16x16x32_bf16 v[70:73], v[212:215], v[98:101], v[70:73]
	v_mfma_f32_16x16x32_bf16 v[66:69], v[212:215], v[114:117], v[66:69]
	v_mfma_f32_16x16x32_bf16 v[150:153], v[162:165], v[102:105], v[86:89]
	v_mfma_f32_16x16x32_bf16 v[154:157], v[162:165], v[118:121], v[82:85]
	v_mfma_f32_16x16x32_bf16 v[158:161], v[216:219], v[102:105], v[70:73]
	v_mfma_f32_16x16x32_bf16 v[162:165], v[216:219], v[118:121], v[66:69]
	s_barrier
	s_nop 1
	ds_read_b128 v[66:69], v0 offset:16384
	ds_read_b128 v[70:73], v0 offset:17408
	ds_read_b128 v[82:85], v142 offset:16384
	ds_read_b128 v[86:89], v142 offset:17408
	ds_read_b128 v[166:169], v143 offset:16384
	ds_read_b128 v[186:189], v143 offset:17408
	ds_read_b128 v[212:215], v144 offset:16384
	ds_read_b128 v[216:219], v144 offset:17408
	s_waitcnt vmcnt(4)
	s_barrier
	s_waitcnt lgkmcnt(0)
	s_waitcnt lgkmcnt(7)
	v_mfma_f32_16x16x32_bf16 v[62:65], v[66:69], v[130:133], v[62:65]
	v_mfma_f32_16x16x32_bf16 v[58:61], v[66:69], v[138:141], v[58:61]
	s_waitcnt lgkmcnt(3)
	v_mfma_f32_16x16x32_bf16 v[46:49], v[166:169], v[130:133], v[46:49]
	v_mfma_f32_16x16x32_bf16 v[42:45], v[166:169], v[138:141], v[42:45]
	v_mfma_f32_16x16x32_bf16 v[62:65], v[70:73], v[134:137], v[62:65]
	v_mfma_f32_16x16x32_bf16 v[58:61], v[70:73], v[146:149], v[58:61]
	v_mfma_f32_16x16x32_bf16 v[54:57], v[82:85], v[130:133], v[54:57]
	v_mfma_f32_16x16x32_bf16 v[50:53], v[82:85], v[138:141], v[50:53]
	s_waitcnt lgkmcnt(2)
	v_mfma_f32_16x16x32_bf16 v[46:49], v[186:189], v[134:137], v[46:49]
	v_mfma_f32_16x16x32_bf16 v[42:45], v[186:189], v[146:149], v[42:45]
	s_waitcnt lgkmcnt(1)
	v_mfma_f32_16x16x32_bf16 v[38:41], v[212:215], v[130:133], v[38:41]
	v_mfma_f32_16x16x32_bf16 v[34:37], v[212:215], v[138:141], v[34:37]
	v_mfma_f32_16x16x32_bf16 v[236:239], v[86:89], v[134:137], v[54:57]
	v_mfma_f32_16x16x32_bf16 v[240:243], v[86:89], v[146:149], v[50:53]
	s_waitcnt lgkmcnt(0)
	v_mfma_f32_16x16x32_bf16 v[130:133], v[216:219], v[134:137], v[38:41]
	v_mfma_f32_16x16x32_bf16 v[134:137], v[216:219], v[146:149], v[34:37]
	v_mfma_f32_16x16x32_bf16 v[30:33], v[66:69], v[98:101], v[30:33]
	v_mfma_f32_16x16x32_bf16 v[26:29], v[66:69], v[114:117], v[26:29]
	v_mfma_f32_16x16x32_bf16 v[14:17], v[166:169], v[98:101], v[14:17]
	v_mfma_f32_16x16x32_bf16 v[10:13], v[166:169], v[114:117], v[10:13]
	v_mfma_f32_16x16x32_bf16 v[30:33], v[70:73], v[102:105], v[30:33]
	v_mfma_f32_16x16x32_bf16 v[26:29], v[70:73], v[118:121], v[26:29]
	v_mfma_f32_16x16x32_bf16 v[22:25], v[82:85], v[98:101], v[22:25]
	v_mfma_f32_16x16x32_bf16 v[18:21], v[82:85], v[114:117], v[18:21]
	v_mfma_f32_16x16x32_bf16 v[14:17], v[186:189], v[102:105], v[14:17]
	v_mfma_f32_16x16x32_bf16 v[10:13], v[186:189], v[118:121], v[10:13]
	v_mfma_f32_16x16x32_bf16 v[6:9], v[212:215], v[98:101], v[6:9]
	v_mfma_f32_16x16x32_bf16 v[2:5], v[212:215], v[114:117], v[2:5]
	v_mfma_f32_16x16x32_bf16 v[138:141], v[86:89], v[102:105], v[22:25]
	v_mfma_f32_16x16x32_bf16 v[146:149], v[86:89], v[118:121], v[18:21]
	v_mfma_f32_16x16x32_bf16 v[166:169], v[216:219], v[102:105], v[6:9]
	v_mfma_f32_16x16x32_bf16 v[186:189], v[216:219], v[118:121], v[2:5]
	v_add_u32_e32 v18, v177, v174
	s_barrier
	s_nop 0
	ds_read_b128 v[2:5], v18
	ds_read_b128 v[6:9], v18 offset:1024
	ds_read_b128 v[212:215], v18 offset:2048
	ds_read_b128 v[216:219], v18 offset:3072
	ds_read_b128 v[18:21], v0 offset:32768
	ds_read_b128 v[22:25], v0 offset:33792
	ds_read_b128 v[34:37], v142 offset:32768
	ds_read_b128 v[38:41], v142 offset:33792
	ds_read_b128 v[50:53], v143 offset:32768
	ds_read_b128 v[54:57], v143 offset:33792
	ds_read_b128 v[248:251], v144 offset:32768
	ds_read_b128 v[196:199], v144 offset:33792
	s_waitcnt vmcnt(2)
	s_barrier
; #define LDA(dst, b, h) for (int m = 0; m < 4; ++m) for (int k = 0; k < 2; ++k) \
;     dst[m][k] = *reinterpret_cast<const bf16x8*>((char*)SA(b, h) + lds_byte(wr * 64 + m * 16 + fr, k * 32 + fq * 8))
; #define LDB(dst, b, h) for (int n = 0; n < 2; ++n) for (int k = 0; k < 2; ++k) \
;     dst[n][k] = *reinterpret_cast<const bf16x8*>((char*)SB(b, h) + lds_byte(wc * 32 + n * 16 + fr, k * 32 + fq * 8))
; #define MMA(ai, bj, At, Bt_) do { __builtin_amdgcn_s_setprio(1); \
;     for (int m = 0; m < 4; ++m) for (int n = 0; n < 2; ++n) for (int k = 0; k < 2; ++k) \
;       acc[ai][bj][m][n] = __builtin_amdgcn_mfma_f32_16x16x32_bf16(At[m][k], Bt_[n][k], acc[ai][bj][m][n], 0, 0, 0); \
;     __builtin_amdgcn_s_setprio(0); } while (0)
; #define WAIT_V(n) asm volatile("s_waitcnt vmcnt(" #n ")" ::: "memory")
; #define WAIT_L(n) asm volatile("s_waitcnt lgkmcnt(" #n ")" ::: "memory")
; #define BAR __builtin_amdgcn_s_barrier()
; #define LDA(dst, b, h) for (int m = 0; m < 4; ++m) for (int k = 0; k < 2; ++k) \
;     dst[m][k] = *reinterpret_cast<const bf16x8*>((char*)SA(b, h) + lds_byte(wr * 64 + m * 16 + fr, k * 32 + fq * 8))
; #define LDB(dst, b, h) for (int n = 0; n < 2; ++n) for (int k = 0; k < 2; ++k) \
;     dst[n][k] = *reinterpret_cast<const bf16x8*>((char*)SB(b, h) + lds_byte(wc * 32 + n * 16 + fr, k * 32 + fq * 8))
; #define MMA(ai, bj, At, Bt_) do { __builtin_amdgcn_s_setprio(1); \
;     for (int m = 0; m < 4; ++m) for (int n = 0; n < 2; ++n) for (int k = 0; k < 2; ++k) \
;       acc[ai][bj][m][n] = __builtin_amdgcn_mfma_f32_16x16x32_bf16(At[m][k], Bt_[n][k], acc[ai][bj][m][n], 0, 0, 0); \
;     __builtin_amdgcn_s_setprio(0); } while (0)
; #define WAIT_V(n) asm volatile("s_waitcnt vmcnt(" #n ")" ::: "memory")
; #define WAIT_L(n) asm volatile("s_waitcnt lgkmcnt(" #n ")" ::: "memory")
; #define BAR __builtin_amdgcn_s_barrier()
; __device__ __forceinline__ void gemm8_rt(const PRef& p, const bf16* __restrict__ A, const bf16* __restrict__ Bt, const int K, const int N, const int epi, const int splitS, float* __restrict__ outp, bf16* shm) {
;     ...
;     { LDB(B0, 1, 0); LDA(At, 1, 0); WAIT_V(2); BAR; WAIT_L(0); MMA(0, 0, At, B0); BAR;
;       LDB(B1, 1, 1); WAIT_V(0); BAR; WAIT_L(0); MMA(0, 1, At, B1); BAR;
;       LDA(At, 1, 1); BAR; WAIT_L(0); MMA(1, 0, At, B0); MMA(1, 1, At, B1); BAR; }
;     if (wr == 0) BAR;
	s_waitcnt lgkmcnt(0)
	s_waitcnt lgkmcnt(7)
	v_mfma_f32_16x16x32_bf16 v[66:69], v[18:21], v[2:5], v[126:129]
	s_waitcnt lgkmcnt(6)
	v_mfma_f32_16x16x32_bf16 v[118:121], v[22:25], v[6:9], v[66:69]
	v_mfma_f32_16x16x32_bf16 v[66:69], v[18:21], v[212:215], v[122:125]
	v_mfma_f32_16x16x32_bf16 v[114:117], v[22:25], v[216:219], v[66:69]
	s_waitcnt lgkmcnt(5)
	v_mfma_f32_16x16x32_bf16 v[66:69], v[34:37], v[2:5], v[220:223]
	s_waitcnt lgkmcnt(4)
	v_mfma_f32_16x16x32_bf16 v[102:105], v[38:41], v[6:9], v[66:69]
	v_mfma_f32_16x16x32_bf16 v[66:69], v[34:37], v[212:215], v[224:227]
	v_mfma_f32_16x16x32_bf16 v[98:101], v[38:41], v[216:219], v[66:69]
	s_waitcnt lgkmcnt(3)
	v_mfma_f32_16x16x32_bf16 v[66:69], v[50:53], v[2:5], v[110:113]
	s_waitcnt lgkmcnt(2)
	v_mfma_f32_16x16x32_bf16 v[86:89], v[54:57], v[6:9], v[66:69]
	v_mfma_f32_16x16x32_bf16 v[66:69], v[50:53], v[212:215], v[106:109]
	v_mfma_f32_16x16x32_bf16 v[82:85], v[54:57], v[216:219], v[66:69]
	s_waitcnt lgkmcnt(1)
	v_mfma_f32_16x16x32_bf16 v[66:69], v[248:251], v[2:5], v[228:231]
	s_waitcnt lgkmcnt(0)
	v_mfma_f32_16x16x32_bf16 v[70:73], v[196:199], v[6:9], v[66:69]
	v_mfma_f32_16x16x32_bf16 v[66:69], v[248:251], v[212:215], v[232:235]
	v_mfma_f32_16x16x32_bf16 v[66:69], v[196:199], v[216:219], v[66:69]
	v_add_u32_e32 v106, v178, v174
	s_barrier
	ds_read_b128 v[220:223], v106
	ds_read_b128 v[224:227], v106 offset:1024
	ds_read_b128 v[228:231], v106 offset:2048
	ds_read_b128 v[232:235], v106 offset:3072
	s_waitcnt vmcnt(0)
	s_barrier
	s_waitcnt lgkmcnt(0)
	s_waitcnt lgkmcnt(3)
	v_mfma_f32_16x16x32_bf16 v[94:97], v[18:21], v[220:223], v[94:97]
	s_waitcnt lgkmcnt(1)
	v_mfma_f32_16x16x32_bf16 v[18:21], v[18:21], v[228:231], v[90:93]
	s_waitcnt lgkmcnt(0)
	v_mfma_f32_16x16x32_bf16 v[122:125], v[22:25], v[232:235], v[18:21]
	v_mfma_f32_16x16x32_bf16 v[18:21], v[34:37], v[220:223], v[150:153]
	v_mfma_f32_16x16x32_bf16 v[110:113], v[38:41], v[224:227], v[18:21]
	v_mfma_f32_16x16x32_bf16 v[18:21], v[34:37], v[228:231], v[154:157]
	v_mfma_f32_16x16x32_bf16 v[106:109], v[38:41], v[232:235], v[18:21]
	v_mfma_f32_16x16x32_bf16 v[18:21], v[50:53], v[220:223], v[78:81]
	v_mfma_f32_16x16x32_bf16 v[126:129], v[22:25], v[224:227], v[94:97]
	v_mfma_f32_16x16x32_bf16 v[94:97], v[54:57], v[224:227], v[18:21]
	v_mfma_f32_16x16x32_bf16 v[18:21], v[50:53], v[228:231], v[74:77]
	v_mfma_f32_16x16x32_bf16 v[90:93], v[54:57], v[232:235], v[18:21]
	v_mfma_f32_16x16x32_bf16 v[18:21], v[248:251], v[220:223], v[158:161]
	v_mfma_f32_16x16x32_bf16 v[78:81], v[196:199], v[224:227], v[18:21]
	v_mfma_f32_16x16x32_bf16 v[18:21], v[248:251], v[228:231], v[162:165]
	v_mfma_f32_16x16x32_bf16 v[74:77], v[196:199], v[232:235], v[18:21]
	s_barrier
	ds_read_b128 v[150:153], v0 offset:49152
	ds_read_b128 v[154:157], v0 offset:50176
	ds_read_b128 v[158:161], v142 offset:49152
	ds_read_b128 v[162:165], v142 offset:50176
	ds_read_b128 v[196:199], v143 offset:49152
	ds_read_b128 v[248:251], v143 offset:50176
	ds_read_b128 v[204:207], v144 offset:49152
	ds_read_b128 v[200:203], v144 offset:50176
	s_barrier
	s_waitcnt lgkmcnt(0)
	s_waitcnt lgkmcnt(7)
	v_mfma_f32_16x16x32_bf16 v[18:21], v[150:153], v[2:5], v[62:65]
	s_waitcnt lgkmcnt(6)
	v_mfma_f32_16x16x32_bf16 v[54:57], v[154:157], v[6:9], v[18:21]
	v_mfma_f32_16x16x32_bf16 v[18:21], v[150:153], v[212:215], v[58:61]
	v_mfma_f32_16x16x32_bf16 v[50:53], v[154:157], v[216:219], v[18:21]
	s_waitcnt lgkmcnt(5)
	v_mfma_f32_16x16x32_bf16 v[18:21], v[158:161], v[2:5], v[236:239]
	s_waitcnt lgkmcnt(4)
	v_mfma_f32_16x16x32_bf16 v[38:41], v[162:165], v[6:9], v[18:21]
	v_mfma_f32_16x16x32_bf16 v[18:21], v[158:161], v[212:215], v[240:243]
	v_mfma_f32_16x16x32_bf16 v[34:37], v[162:165], v[216:219], v[18:21]
	s_waitcnt lgkmcnt(3)
	v_mfma_f32_16x16x32_bf16 v[18:21], v[196:199], v[2:5], v[46:49]
	s_waitcnt lgkmcnt(1)
	v_mfma_f32_16x16x32_bf16 v[2:5], v[204:207], v[2:5], v[130:133]
	v_mfma_f32_16x16x32_bf16 v[22:25], v[248:251], v[6:9], v[18:21]
	v_mfma_f32_16x16x32_bf16 v[18:21], v[196:199], v[212:215], v[42:45]
	s_waitcnt lgkmcnt(0)
	v_mfma_f32_16x16x32_bf16 v[6:9], v[200:203], v[6:9], v[2:5]
	v_mfma_f32_16x16x32_bf16 v[2:5], v[204:207], v[212:215], v[134:137]
	v_mfma_f32_16x16x32_bf16 v[18:21], v[248:251], v[216:219], v[18:21]
	v_mfma_f32_16x16x32_bf16 v[2:5], v[200:203], v[216:219], v[2:5]
	v_mfma_f32_16x16x32_bf16 v[26:29], v[150:153], v[228:231], v[26:29]
	v_mfma_f32_16x16x32_bf16 v[58:61], v[154:157], v[232:235], v[26:29]
	v_mfma_f32_16x16x32_bf16 v[26:29], v[158:161], v[220:223], v[138:141]
	v_mfma_f32_16x16x32_bf16 v[46:49], v[162:165], v[224:227], v[26:29]
	v_mfma_f32_16x16x32_bf16 v[26:29], v[158:161], v[228:231], v[146:149]
	v_mfma_f32_16x16x32_bf16 v[10:13], v[196:199], v[228:231], v[10:13]
	v_mfma_f32_16x16x32_bf16 v[30:33], v[150:153], v[220:223], v[30:33]
	v_mfma_f32_16x16x32_bf16 v[42:45], v[162:165], v[232:235], v[26:29]
	v_mfma_f32_16x16x32_bf16 v[14:17], v[196:199], v[220:223], v[14:17]
	v_mfma_f32_16x16x32_bf16 v[26:29], v[248:251], v[232:235], v[10:13]
	v_mfma_f32_16x16x32_bf16 v[10:13], v[204:207], v[220:223], v[166:169]
	v_mfma_f32_16x16x32_bf16 v[62:65], v[154:157], v[224:227], v[30:33]
	v_mfma_f32_16x16x32_bf16 v[30:33], v[248:251], v[224:227], v[14:17]
	v_mfma_f32_16x16x32_bf16 v[14:17], v[200:203], v[224:227], v[10:13]
	v_mfma_f32_16x16x32_bf16 v[10:13], v[204:207], v[228:231], v[186:189]
	v_mfma_f32_16x16x32_bf16 v[10:13], v[200:203], v[232:235], v[10:13]
	s_barrier
	s_and_saveexec_b64 s[0:1], s[8:9]
	s_cbranch_execz .LBB0_351
	s_barrier
